# full grid barrier: the last XCC leader bumps every XCC generation word itself; other leaders wait on their own word (one polling hop less on release)
# speedup vs baseline: 1.0058x; 1.0058x over previous
; #define LAS __attribute__((address_space(3)))
; __global__ void __launch_bounds__(NTHREADS, 2) mega_fwd(Args args) {
;     extern __shared__ __attribute__((aligned(16))) unsigned char lds[];
;     cg::grid_group grid = cg::this_grid();
;     ...
;     if (threadIdx.x < 16) ((volatile LAS unsigned*)((LAS unsigned char*)lds + LDS_MISC))[threadIdx.x] = 0u;
;     __syncthreads();
_Z8mega_fwd4Args:
	s_mov_b64 s[90:91], s[0:1]
	s_load_dwordx2 s[56:57], s[0:1], 0xc8
	s_add_u32 s0, s90, 0xc8
	s_addc_u32 s1, s91, 0
	v_and_b32_e32 v203, 0x3ff, v0
	v_writelane_b32 v255, s0, 0
	s_mov_b32 s83, s2
	v_cmp_gt_u32_e32 vcc, 16, v203
	v_writelane_b32 v255, s1, 1
	s_and_saveexec_b64 s[4:5], vcc
	v_lshl_add_u32 v1, v203, 2, 0
	v_add_u32_e32 v1, 0x22000, v1
	v_mov_b32_e32 v2, 0
	ds_write_b32 v1, v2
	s_or_b64 exec, exec, s[4:5]
	s_waitcnt lgkmcnt(0)
	s_barrier
	s_load_dwordx4 s[4:7], s[90:91], 0x0
	s_load_dwordx4 s[92:95], s[90:91], 0x40
	s_cmp_lt_u32 s57, 2
	s_cselect_b64 s[0:1], -1, 0
	v_writelane_b32 v255, s0, 2
	v_lshrrev_b32_e32 v1, 20, v0
	v_lshrrev_b32_e32 v0, 10, v0
	v_writelane_b32 v255, s1, 3
	v_or_b32_e32 v0, v0, v1
	s_movk_i32 s0, 0x3ff
	v_and_or_b32 v0, v0, s0, v203
	s_waitcnt lgkmcnt(0)
	s_add_u32 s0, s4, 0xc00
	v_writelane_b32 v255, s0, 4
	s_mov_b64 s[2:3], s[6:7]
	v_writelane_b32 v255, s0, 5
	s_mov_b32 s69, 0
	v_mbcnt_lo_u32_b32 v1, -1, 0
	v_writelane_b32 v255, s1, 6
	v_writelane_b32 v255, s2, 7
	v_writelane_b32 v255, s3, 8
	s_addc_u32 s0, s5, 0
	v_writelane_b32 v255, s0, 9
	s_load_dwordx2 s[0:1], s[90:91], 0x60
	s_load_dwordx4 s[4:7], s[90:91], 0xb8
	v_mov_b32_e32 v193, 0
	v_mov_b32_e32 v212, 0x358637bd
	s_mov_b32 s89, 0xf800000
	s_waitcnt lgkmcnt(0)
	s_getreg_b32 s100, hwreg(HW_REG_XCC_ID, 0, 4)
	s_add_i32 s100, s100, 1
	s_lshl_b32 s101, s83, 2
	s_add_i32 s101, s101, 0xe208000
	v_mov_b32_e32 v245, s101
	v_mov_b32_e32 v246, s100
	global_store_dword v245, v246, s[6:7]
	s_mov_b32 s100, 0
	s_mov_b32 s101, 0
	v_writelane_b32 v255, s0, 10
	v_mov_b32_e32 v213, 0x260
	v_mov_b32_e32 v244, 1
	v_writelane_b32 v255, s1, 11
	s_load_dwordx2 s[0:1], s[90:91], 0x70
	s_mov_b32 s81, 0x10000
	s_mov_b32 s57, 0xbfb8aa3b
	s_movk_i32 s3, 0x1600
	s_mov_b32 s73, 0x80000
	s_waitcnt lgkmcnt(0)
	v_writelane_b32 v255, s0, 12
	s_mov_b32 s33, 0x90000
	s_mov_b32 s80, 0xa0000
	v_writelane_b32 v255, s1, 13
	s_load_dwordx2 s[0:1], s[90:91], 0x50
	s_mov_b32 s96, 0xb0000
	s_mov_b32 s97, 0x800000
	s_mov_b32 s52, 0x3f317217
	s_mov_b32 s53, 0x7f800000
	s_waitcnt lgkmcnt(0)
	v_writelane_b32 v255, s0, 14
	s_mov_b32 s54, 0x40000
	s_mov_b32 s55, 0x48000
	v_writelane_b32 v255, s1, 15
	v_cmp_eq_u32_e64 s[0:1], 0, v0
	s_mov_b32 s86, 0x50000
	s_mov_b32 s87, 0x58000
	v_writelane_b32 v255, s0, 16
	v_mbcnt_hi_u32_b32 v215, -1, v1
	v_mov_b64_e32 v[242:243], 0x580
	v_writelane_b32 v255, s1, 17
	s_mov_b32 s0, s69
	v_writelane_b32 v255, s0, 18
	v_mov_b64_e32 v[196:197], 0x57f
	v_mov_b64_e32 v[198:199], 0x100
	v_writelane_b32 v255, s1, 19
	v_writelane_b32 v255, s4, 20
	v_mov_b64_e32 v[200:201], 0xff
	v_mov_b32_e32 v216, 0x41b17218
	v_writelane_b32 v255, s5, 21
	v_writelane_b32 v255, s6, 22
	v_writelane_b32 v255, s7, 23
	v_writelane_b32 v255, s90, 24
	v_mov_b32_e32 v217, 0xff800000
	s_mov_b32 s88, 0x41000000
	v_writelane_b32 v255, s91, 25
	v_writelane_b32 v255, s83, 26
	v_writelane_b32 v255, s92, 27
	s_mov_b64 s[44:45], -1
	s_mov_b64 s[76:77], 0x80
	v_writelane_b32 v255, s93, 28
	v_writelane_b32 v255, s94, 29
	s_mov_b64 s[46:47], 0x20000
	s_mov_b64 s[58:59], 0xba40000
	s_mov_b64 s[62:63], 0xca20000
	v_writelane_b32 v255, s95, 30
	s_branch .LBB0_6

; #define GSYNC() do { LAS unsigned char* l_ = (LAS unsigned char*)lds; asm volatile("" : "+s"(l_)); unsigned char* w_ = args.ws; asm volatile("" : "+s"(w_)); int t_ = threadIdx.x; asm volatile("" : "+v"(t_)); xcd_barrier((unsigned*)(w_ + WS_CTL), (volatile LAS unsigned*)(l_ + LDS_MISC), __builtin_amdgcn_readfirstlane(t_ >> 6), t_ & 63); } while (0)
; __global__ void __launch_bounds__(NTHREADS, 2) mega_fwd(Args args) {
;     ...
;     for (int l = 0; l < DEPTH; ++l) {
;     ...
;         GSYNC();
;     }
.LBB0_5:
	s_add_i32 s101, s101, 1
	s_mov_b32 s0, 1
	v_writelane_b32 v255, s0, 18
	s_mov_b64 s[44:45], 0
	s_waitcnt lgkmcnt(0)
	v_writelane_b32 v255, s1, 19
	s_barrier
	v_readlane_b32 s0, v255, 33
	v_readlane_b32 s1, v255, 34
	s_and_b64 vcc, exec, s[0:1]
	s_cbranch_vccz .LBB0_6
	s_getpc_b64 s[98:99]

; __device__ __forceinline__ unsigned xb_ld_u(unsigned* p) { return (unsigned)__builtin_amdgcn_readfirstlane((int)__hip_atomic_load(p, RLX_AGENT)); }
; __device__ __forceinline__ unsigned xb_add_u(unsigned* p, unsigned v, int lane) { unsigned r = 0u; if (lane == 0) r = __hip_atomic_fetch_add(p, v, RLX_AGENT); return (unsigned)__builtin_amdgcn_readfirstlane((int)r); }
; #define XB_SPIN_U(cond, bar) do { unsigned _sp = 0; while (cond) { __builtin_amdgcn_s_sleep(1); if (++_sp > XB_SPIN_CAP) { if (lane == 0) atomicAdd(&(bar)[XB_TMO], 1u); break; } } } while (0)
; __device__ __forceinline__ void xcd_barrier(unsigned* bar, volatile __attribute__((address_space(3))) unsigned* st, int wave, int lane) {
;     ...
;         const unsigned old = xb_add_u(&bar[XB_XSUB(x)], 1u, lane), gen = old / nloc;
;         if (old + 1u == (gen + 1u) * nloc) {
;             __builtin_amdgcn_fence(__ATOMIC_RELEASE, "agent");
;             asm volatile("s_waitcnt vmcnt(0)" ::: "memory");
;             const unsigned og = xb_add_u(&bar[XB_TOP], 1u, lane), tg = og / nx;
;             if (og + 1u == (tg + 1u) * nx) (void)xb_add_u(&bar[XB_TOPGEN], 1u, lane);
;             else XB_SPIN_U(xb_ld_u(&bar[XB_TOPGEN]) == tg, bar);
.LBB0_107:
	s_or_b64 exec, exec, s[6:7]
	v_cvt_f32_u32_e32 v3, v0
	v_cmp_ne_u32_e32 vcc, 0, v1
	s_waitcnt vmcnt(0) lgkmcnt(0)
	v_readfirstlane_b32 s2, v2
	v_sub_u32_e32 v2, 0, v0
	v_rcp_iflag_f32_e32 v3, v3
	s_add_i32 s8, s2, 1
	s_mov_b64 s[22:23], 0
	s_mov_b64 s[20:21], 0
	v_mul_f32_e32 v1, 0x4f7ffffe, v3
	v_cvt_u32_f32_e32 v1, v1
	s_mov_b64 s[18:19], 0
	v_mul_lo_u32 v2, v2, v1
	v_mul_hi_u32 v2, v1, v2
	v_add_u32_e32 v1, v1, v2
	v_mul_hi_u32 v1, s2, v1
	v_mul_lo_u32 v2, v1, v0
	v_sub_u32_e32 v2, s2, v2
	v_add_u32_e32 v3, 1, v1
	v_cmp_ge_u32_e64 s[6:7], v2, v0
	s_nop 1
	v_cndmask_b32_e64 v1, v1, v3, s[6:7]
	v_sub_u32_e32 v3, v2, v0
	v_cndmask_b32_e64 v2, v2, v3, s[6:7]
	v_add_u32_e32 v3, 1, v1
	v_cmp_ge_u32_e64 s[6:7], v2, v0
	s_nop 1
	v_cndmask_b32_e64 v1, v1, v3, s[6:7]
	v_mad_u64_u32 v[2:3], s[6:7], v0, v1, v[0:1]
	v_cmp_ne_u32_e64 s[6:7], s8, v2
	s_and_b64 s[8:9], s[6:7], exec
	s_cbranch_scc0 .Lrel_last_0
	s_add_u32 s8, s1, 0x2400
	s_addc_u32 s9, s0, 0
	v_mov_b32_e32 v246, s8
	v_mov_b32_e32 v247, s9
	s_mov_b32 s8, 0
	s_add_i32 vcc_lo, s101, 1
.Lrel_spin_0:
	global_load_dword v245, v[246:247], off sc1
	s_add_i32 s8, s8, 1
	s_waitcnt vmcnt(0)
	v_readfirstlane_b32 s9, v245
	s_nop 0
	s_cmp_eq_u32 s9, vcc_lo
	s_cbranch_scc1 .Lrel_done_0
	s_sleep 1
	s_cmp_lt_u32 s8, 0x400000
	s_cbranch_scc1 .Lrel_spin_0

; __device__ __forceinline__ unsigned xb_ld_u(unsigned* p) { return (unsigned)__builtin_amdgcn_readfirstlane((int)__hip_atomic_load(p, RLX_AGENT)); }
; __device__ __forceinline__ unsigned xb_add_u(unsigned* p, unsigned v, int lane) { unsigned r = 0u; if (lane == 0) r = __hip_atomic_fetch_add(p, v, RLX_AGENT); return (unsigned)__builtin_amdgcn_readfirstlane((int)r); }
; #define XB_SPIN_U(cond, bar) do { unsigned _sp = 0; while (cond) { __builtin_amdgcn_s_sleep(1); if (++_sp > XB_SPIN_CAP) { if (lane == 0) atomicAdd(&(bar)[XB_TMO], 1u); break; } } } while (0)
; __device__ __forceinline__ void xcd_barrier(unsigned* bar, volatile __attribute__((address_space(3))) unsigned* st, int wave, int lane) {
;     ...
;             const unsigned og = xb_add_u(&bar[XB_TOP], 1u, lane), tg = og / nx;
;             if (og + 1u == (tg + 1u) * nx) (void)xb_add_u(&bar[XB_TOPGEN], 1u, lane);
;             else XB_SPIN_U(xb_ld_u(&bar[XB_TOPGEN]) == tg, bar);
;             __builtin_amdgcn_fence(__ATOMIC_ACQUIRE, "agent");
;             (void)xb_add_u(&bar[XB_XGEN(x)], 1u, lane);
;             asm volatile("s_waitcnt vmcnt(0)" ::: "memory");
.Lrel_last_0:
	v_readlane_b32 s8, v255, 22
	v_readlane_b32 s9, v255, 23
	v_lshlrev_b32_e32 v245, 8, v215
	v_add_u32_e32 v245, 0xe202400, v245
	s_mov_b64 exec, 0xffff
	s_nop 3
	global_atomic_add v245, v244, s[8:9]
	s_mov_b64 exec, -1
	s_and_saveexec_b64 s[8:9], s[6:7]
	s_xor_b64 s[16:17], exec, s[8:9]
	s_cbranch_execnz .LBB0_112
	s_or_saveexec_b64 s[6:7], s[16:17]
	v_mov_b64_e32 v[0:1], 0x200
	s_xor_b64 exec, exec, s[6:7]
	s_cbranch_execnz .LBB0_127

; __device__ __forceinline__ unsigned xb_add_u(unsigned* p, unsigned v, int lane) { unsigned r = 0u; if (lane == 0) r = __hip_atomic_fetch_add(p, v, RLX_AGENT); return (unsigned)__builtin_amdgcn_readfirstlane((int)r); }
; __device__ __forceinline__ void xcd_barrier(unsigned* bar, volatile __attribute__((address_space(3))) unsigned* st, int wave, int lane) {
;     ...
;             __builtin_amdgcn_fence(__ATOMIC_ACQUIRE, "agent");
;             (void)xb_add_u(&bar[XB_XGEN(x)], 1u, lane);
;             asm volatile("s_waitcnt vmcnt(0)" ::: "memory");
.LBB0_130:
	s_waitcnt vmcnt(0) lgkmcnt(0)
	s_nop 0
	s_and_b64 exec, exec, s[4:5]
	s_cbranch_execz .LBB0_132
	v_mov_b32_e32 v0, s1
	v_add_co_u32_e32 v0, vcc, 0x2000, v0
	v_mov_b32_e32 v1, s0
	s_nop 0
	v_addc_co_u32_e32 v1, vcc, 0, v1, vcc
	s_nop 0

; #define GSYNC() do { LAS unsigned char* l_ = (LAS unsigned char*)lds; asm volatile("" : "+s"(l_)); unsigned char* w_ = args.ws; asm volatile("" : "+s"(w_)); int t_ = threadIdx.x; asm volatile("" : "+v"(t_)); xcd_barrier((unsigned*)(w_ + WS_CTL), (volatile LAS unsigned*)(l_ + LDS_MISC), __builtin_amdgcn_readfirstlane(t_ >> 6), t_ & 63); } while (0)
; __global__ void __launch_bounds__(NTHREADS, 2) mega_fwd(Args args) {
;     ...
;     for (int l = 0; l < DEPTH; ++l) {
;     ...
;         { PHASE_PTRS MKFRAME
;         prologue(F, args, l); }
;     ...
;         if (gridDim.y > 1) grid.sync(); else GSYNC();
;         {   PHASE_PTRS
;             pg8::Gemm g{XB, (const bf16*)(ws + WS_W1A), M, 2 * FFH, DM, DM, DM}; pg8::StaticOrder S; S.init(M, 2 * FFH, G_, bx_);
.LBB0_134:
	s_add_i32 s101, s101, 1
	s_mov_b64 s[4:5], 0
	s_waitcnt lgkmcnt(0)
	s_barrier
	v_readlane_b32 vcc_lo, v255, 22
	v_readlane_b32 vcc_hi, v255, 23
	v_lshlrev_b32_e32 v245, 2, v215
	v_and_b32_e32 v246, 28, v245
	v_add_u32_e32 v245, 0xe208000, v245
	v_add_u32_e32 v246, 0xe208000, v246
	s_nop 3
	global_load_dword v247, v246, vcc
	global_load_dword v248, v245, vcc
	global_load_dword v249, v245, vcc offset:256
	global_load_dword v250, v245, vcc offset:512
	global_load_dword v251, v245, vcc offset:768
	s_waitcnt vmcnt(0)
	v_xor_b32_e32 v248, v248, v247
	v_xor_b32_e32 v249, v249, v247
	v_xor_b32_e32 v250, v250, v247
	v_xor_b32_e32 v251, v251, v247
	v_or3_b32 v248, v248, v249, v250
	v_or_b32_e32 v248, v248, v251
	v_cmp_ne_u32_e32 vcc, 0, v248
	s_nop 1
	s_cmp_eq_u64 vcc, 0
	s_cselect_b32 s100, 1, 0

; #define GSYNC() do { LAS unsigned char* l_ = (LAS unsigned char*)lds; asm volatile("" : "+s"(l_)); unsigned char* w_ = args.ws; asm volatile("" : "+s"(w_)); int t_ = threadIdx.x; asm volatile("" : "+v"(t_)); xcd_barrier((unsigned*)(w_ + WS_CTL), (volatile LAS unsigned*)(l_ + LDS_MISC), __builtin_amdgcn_readfirstlane(t_ >> 6), t_ & 63); } while (0)
; __global__ void __launch_bounds__(NTHREADS, 2) mega_fwd(Args args) {
;     ...
;         GSYNC();
;         {   PHASE_PTRS
;             pg8::Gemm g{ACT, (const bf16*)(ws + WS_W1B), M, DM, FFH, FFH, FFH}; pg8::StaticOrder S; S.init(M, DM, G_, bx_);
;             EpiRes E{XB, SSQ, 0.5f};
;             pg8::gemm_phase<EpiRes, pg8::StaticOrder, true, true>(ldsp, g, S, E);
.LBB0_255:
	s_add_i32 s101, s101, 1
	v_readlane_b32 s8, v255, 20
	v_readlane_b32 s9, v255, 21
	v_readlane_b32 s10, v255, 22
	v_readlane_b32 s11, v255, 23
	s_mov_b32 s0, s83
	s_mov_b32 s1, s56
	s_mov_b32 s18, s69
	s_mov_b64 s[4:5], s[10:11]
	s_mov_b64 s[6:7], s[8:9]
	s_waitcnt lgkmcnt(0)
	s_barrier
	v_mov_b32_e32 v12, v203
	s_cmpk_lt_i32 s0, 0x100
	s_cselect_b64 s[6:7], -1, 0
	s_cmpk_gt_i32 s0, 0xff
	v_readfirstlane_b32 s16, v12
	s_cbranch_scc1 .LBB0_261
	s_ashr_i32 s2, s0, 31
	s_lshr_b32 s2, s2, 29
	s_add_i32 s2, s0, s2
	s_and_b32 s8, s2, -8
	s_sub_i32 s12, s0, s8
	s_cmp_gt_i32 s12, -1
	s_mov_b64 s[10:11], -1
	s_cbranch_scc0 .LBB0_258
	s_lshl_b32 s13, s12, 5
	s_mov_b64 s[10:11], 0

; __device__ __forceinline__ unsigned xb_ld_u(unsigned* p) { return (unsigned)__builtin_amdgcn_readfirstlane((int)__hip_atomic_load(p, RLX_AGENT)); }
; __device__ __forceinline__ unsigned xb_add_u(unsigned* p, unsigned v, int lane) { unsigned r = 0u; if (lane == 0) r = __hip_atomic_fetch_add(p, v, RLX_AGENT); return (unsigned)__builtin_amdgcn_readfirstlane((int)r); }
; #define XB_SPIN_U(cond, bar) do { unsigned _sp = 0; while (cond) { __builtin_amdgcn_s_sleep(1); if (++_sp > XB_SPIN_CAP) { if (lane == 0) atomicAdd(&(bar)[XB_TMO], 1u); break; } } } while (0)
; __device__ __forceinline__ void xcd_barrier(unsigned* bar, volatile __attribute__((address_space(3))) unsigned* st, int wave, int lane) {
;     ...
;         const unsigned old = xb_add_u(&bar[XB_XSUB(x)], 1u, lane), gen = old / nloc;
;         if (old + 1u == (gen + 1u) * nloc) {
;             __builtin_amdgcn_fence(__ATOMIC_RELEASE, "agent");
;             asm volatile("s_waitcnt vmcnt(0)" ::: "memory");
;             const unsigned og = xb_add_u(&bar[XB_TOP], 1u, lane), tg = og / nx;
;             if (og + 1u == (tg + 1u) * nx) (void)xb_add_u(&bar[XB_TOPGEN], 1u, lane);
;             else XB_SPIN_U(xb_ld_u(&bar[XB_TOPGEN]) == tg, bar);
.LBB0_342:
	s_or_b64 exec, exec, s[6:7]
	v_cvt_f32_u32_e32 v3, v0
	v_cmp_ne_u32_e32 vcc, 0, v1
	s_waitcnt vmcnt(0) lgkmcnt(0)
	v_readfirstlane_b32 s2, v2
	v_sub_u32_e32 v2, 0, v0
	v_rcp_iflag_f32_e32 v3, v3
	s_add_i32 s14, s2, 1
	s_mov_b64 s[20:21], 0
	s_mov_b64 s[18:19], 0
	v_mul_f32_e32 v1, 0x4f7ffffe, v3
	v_cvt_u32_f32_e32 v1, v1
	s_mov_b64 s[16:17], 0
	v_mul_lo_u32 v2, v2, v1
	v_mul_hi_u32 v2, v1, v2
	v_add_u32_e32 v1, v1, v2
	v_mul_hi_u32 v1, s2, v1
	v_mul_lo_u32 v2, v1, v0
	v_sub_u32_e32 v2, s2, v2
	v_add_u32_e32 v3, 1, v1
	v_cmp_ge_u32_e64 s[6:7], v2, v0
	s_nop 1
	v_cndmask_b32_e64 v1, v1, v3, s[6:7]
	v_sub_u32_e32 v3, v2, v0
	v_cndmask_b32_e64 v2, v2, v3, s[6:7]
	v_add_u32_e32 v3, 1, v1
	v_cmp_ge_u32_e64 s[6:7], v2, v0
	s_nop 1
	v_cndmask_b32_e64 v1, v1, v3, s[6:7]
	v_mad_u64_u32 v[2:3], s[6:7], v0, v1, v[0:1]
	v_cmp_ne_u32_e64 s[6:7], s14, v2
	s_and_b64 s[14:15], s[6:7], exec
	s_cbranch_scc0 .Lrel_last_2
	s_add_u32 s14, s1, 0x2400
	s_addc_u32 s15, s0, 0
	v_mov_b32_e32 v246, s14
	v_mov_b32_e32 v247, s15
	s_mov_b32 s14, 0
	s_add_i32 vcc_lo, s101, 1
.Lrel_spin_2:
	global_load_dword v245, v[246:247], off sc1
	s_add_i32 s14, s14, 1
	s_waitcnt vmcnt(0)
	v_readfirstlane_b32 s15, v245
	s_nop 0
	s_cmp_eq_u32 s15, vcc_lo
	s_cbranch_scc1 .Lrel_done_2
	s_sleep 1
	s_cmp_lt_u32 s14, 0x400000
	s_cbranch_scc1 .Lrel_spin_2

; __device__ __forceinline__ unsigned xb_ld_u(unsigned* p) { return (unsigned)__builtin_amdgcn_readfirstlane((int)__hip_atomic_load(p, RLX_AGENT)); }
; __device__ __forceinline__ unsigned xb_add_u(unsigned* p, unsigned v, int lane) { unsigned r = 0u; if (lane == 0) r = __hip_atomic_fetch_add(p, v, RLX_AGENT); return (unsigned)__builtin_amdgcn_readfirstlane((int)r); }
; #define XB_SPIN_U(cond, bar) do { unsigned _sp = 0; while (cond) { __builtin_amdgcn_s_sleep(1); if (++_sp > XB_SPIN_CAP) { if (lane == 0) atomicAdd(&(bar)[XB_TMO], 1u); break; } } } while (0)
; __device__ __forceinline__ void xcd_barrier(unsigned* bar, volatile __attribute__((address_space(3))) unsigned* st, int wave, int lane) {
;     ...
;             const unsigned og = xb_add_u(&bar[XB_TOP], 1u, lane), tg = og / nx;
;             if (og + 1u == (tg + 1u) * nx) (void)xb_add_u(&bar[XB_TOPGEN], 1u, lane);
;             else XB_SPIN_U(xb_ld_u(&bar[XB_TOPGEN]) == tg, bar);
;             __builtin_amdgcn_fence(__ATOMIC_ACQUIRE, "agent");
;             (void)xb_add_u(&bar[XB_XGEN(x)], 1u, lane);
;             asm volatile("s_waitcnt vmcnt(0)" ::: "memory");
.Lrel_last_2:
	v_readlane_b32 s14, v255, 22
	v_readlane_b32 s15, v255, 23
	v_lshlrev_b32_e32 v245, 8, v215
	v_add_u32_e32 v245, 0xe202400, v245
	s_mov_b64 exec, 0xffff
	s_nop 3
	global_atomic_add v245, v244, s[14:15]
	s_mov_b64 exec, -1
	s_and_saveexec_b64 s[14:15], s[6:7]
	s_xor_b64 s[14:15], exec, s[14:15]
	s_cbranch_execnz .LBB0_347
	s_or_saveexec_b64 s[6:7], s[14:15]
	v_mov_b64_e32 v[0:1], 0x200
	s_xor_b64 exec, exec, s[6:7]
	s_cbranch_execnz .LBB0_362

; #define GSYNC() do { LAS unsigned char* l_ = (LAS unsigned char*)lds; asm volatile("" : "+s"(l_)); unsigned char* w_ = args.ws; asm volatile("" : "+s"(w_)); int t_ = threadIdx.x; asm volatile("" : "+v"(t_)); xcd_barrier((unsigned*)(w_ + WS_CTL), (volatile LAS unsigned*)(l_ + LDS_MISC), __builtin_amdgcn_readfirstlane(t_ >> 6), t_ & 63); } while (0)
; __global__ void __launch_bounds__(NTHREADS, 2) mega_fwd(Args args) {
;     ...
;         GSYNC();
;         {   PHASE_PTRS
;             pg8::Gemm g{XB, (const bf16*)(ws + WS_WIN), M, NINP, DM, DM, DM}; pg8::StaticOrder S; S.init(M, NINP, G_, bx_);
;             EpiWin E{ws, (const float*)(ws + WS_LB) + l * 512, args.in[10] + l * 8};
;             pg8::gemm_phase<EpiWin, pg8::StaticOrder, true, true>(ldsp, g, S, E);
.LBB0_369:
	s_add_i32 s101, s101, 1
	v_readlane_b32 s4, v255, 20
	s_mov_b32 s89, s83
	v_readlane_b32 s5, v255, 21
	s_waitcnt lgkmcnt(0)
	s_barrier
	s_mov_b32 s74, s56
	s_mov_b32 s16, s69
	v_readlane_b32 s6, v255, 22
	v_readlane_b32 s7, v255, 23
	s_mov_b64 s[0:1], s[4:5]
	v_mov_b32_e32 v14, v203
	s_cmpk_lt_i32 s89, 0x3c0
	s_cselect_b64 s[4:5], -1, 0
	s_cmpk_gt_i32 s89, 0x3bf
	v_readfirstlane_b32 s17, v14
	s_cbranch_scc1 .LBB0_371
	s_ashr_i32 s0, s89, 31
	s_lshr_b32 s0, s0, 29
	s_add_i32 s0, s89, s0
	s_ashr_i32 s1, s0, 3
	s_and_b32 s0, s0, -8
	s_sub_i32 s0, s89, s0
	s_cmp_lt_i32 s0, 0
	s_movk_i32 s2, 0x79
	s_cselect_b32 s2, s2, 0x78
	s_mul_i32 s0, s0, s2
	s_add_i32 s0, s0, s1
	s_mul_hi_i32 s1, s0, 0x88888889
	s_add_i32 s1, s1, s0
	s_lshr_b32 s2, s1, 31
	s_ashr_i32 s1, s1, 6
	s_add_i32 s1, s1, s2
	s_lshl_b32 s2, s1, 3
	s_mulk_i32 s1, 0x78
	s_sub_i32 s0, s0, s1
	s_bfe_i32 s1, s0, 0x80000
	s_bfe_u32 s1, s1, 0x3000c
	s_add_i32 s1, s0, s1
	s_bfe_i32 s8, s1, 0x80000
	s_and_b32 s1, s1, 0xf8
	s_sub_i32 s0, s0, s1
	s_sext_i32_i16 s9, s8
	s_sext_i32_i8 s0, s0
	s_add_i32 s8, s2, s0
	s_ashr_i32 s10, s9, 3

; #define GSYNC() do { LAS unsigned char* l_ = (LAS unsigned char*)lds; asm volatile("" : "+s"(l_)); unsigned char* w_ = args.ws; asm volatile("" : "+s"(w_)); int t_ = threadIdx.x; asm volatile("" : "+v"(t_)); xcd_barrier((unsigned*)(w_ + WS_CTL), (volatile LAS unsigned*)(l_ + LDS_MISC), __builtin_amdgcn_readfirstlane(t_ >> 6), t_ & 63); } while (0)
; __global__ void __launch_bounds__(NTHREADS, 2) mega_fwd(Args args) {
;     ...
;         GSYNC();
;         { PHASE_PTRS MKFRAME
;           for (int u = F.vcu; u < 1024 + 16; u += F.G) { if (u < 1024) hgrn_pass1_unit(F, u); else fox_cumsum_unit(F, u - 1024); } }
.LBB0_513:
	s_add_i32 s101, s101, 1
	v_readlane_b32 s4, v255, 20
	s_mov_b32 s44, s83
	s_mov_b32 s0, s56
	v_readlane_b32 s5, v255, 21
	v_readlane_b32 s6, v255, 22
	v_readlane_b32 s7, v255, 23
	s_waitcnt lgkmcnt(0)
	s_barrier
	s_mov_b32 s1, s69
	s_mov_b64 s[26:27], s[6:7]
	s_mov_b64 s[48:49], s[4:5]
	v_mov_b32_e32 v0, v203
	s_and_b32 s2, s0, 7
	s_cmp_lg_u32 s2, 0
	v_readfirstlane_b32 s2, v0
	s_cbranch_scc0 .LBB0_515
	s_cmpk_gt_i32 s44, 0x40f
	s_cbranch_scc0 .LBB0_516
	s_branch .LBB0_532

; #define GSYNC() do { LAS unsigned char* l_ = (LAS unsigned char*)lds; asm volatile("" : "+s"(l_)); unsigned char* w_ = args.ws; asm volatile("" : "+s"(w_)); int t_ = threadIdx.x; asm volatile("" : "+v"(t_)); xcd_barrier((unsigned*)(w_ + WS_CTL), (volatile LAS unsigned*)(l_ + LDS_MISC), __builtin_amdgcn_readfirstlane(t_ >> 6), t_ & 63); } while (0)
; __global__ void __launch_bounds__(NTHREADS, 2) mega_fwd(Args args) {
;     ...
;         GSYNC();
;         { PHASE_PTRS MKFRAME fox_bounds(F); hgrn_pass2(F); }
.LBB0_600:
	s_add_i32 s101, s101, 1
	s_mov_b32 s0, s83
	s_mov_b32 s1, s56
	s_mov_b32 s2, s69
	v_readlane_b32 s4, v255, 20
	s_waitcnt lgkmcnt(0)
	s_barrier
	v_readlane_b32 s5, v255, 21
	v_readlane_b32 s6, v255, 22
	v_readlane_b32 s7, v255, 23
	s_mov_b64 s[10:11], s[6:7]
	s_mov_b64 s[8:9], s[4:5]
	v_mov_b32_e32 v5, v203
	s_and_b32 s2, s1, 7
	s_cmp_eq_u32 s2, 0
	v_readfirstlane_b32 s2, v5
	s_cbranch_scc0 .LBB0_602
	s_ashr_i32 s5, s0, 31
	s_lshr_b32 s5, s5, 29
	s_add_i32 s5, s0, s5
	s_ashr_i32 s6, s5, 3
	s_and_b32 s5, s5, -8
	s_ashr_i32 s4, s1, 3
	s_sub_i32 s0, s0, s5
	s_mul_i32 s0, s4, s0
	s_add_i32 s0, s0, s6

; #define GSYNC() do { LAS unsigned char* l_ = (LAS unsigned char*)lds; asm volatile("" : "+s"(l_)); unsigned char* w_ = args.ws; asm volatile("" : "+s"(w_)); int t_ = threadIdx.x; asm volatile("" : "+v"(t_)); xcd_barrier((unsigned*)(w_ + WS_CTL), (volatile LAS unsigned*)(l_ + LDS_MISC), __builtin_amdgcn_readfirstlane(t_ >> 6), t_ & 63); } while (0)
; __global__ void __launch_bounds__(NTHREADS, 2) mega_fwd(Args args) {
;     ...
;         GSYNC();
;         { PHASE_PTRS MKFRAME for (int u = F.vcu; u < 512; u += F.G) hgrn_pass3_unit(F, args.in[9] + l * 128, u); }
.LBB0_692:
	s_add_i32 s101, s101, 1
	v_readlane_b32 s4, v255, 20
	s_mov_b32 s0, s83
	s_mov_b32 s1, s56
	v_readlane_b32 s6, v255, 22
	v_readlane_b32 s7, v255, 23
	s_waitcnt lgkmcnt(0)
	s_barrier
	s_mov_b32 s2, s69
	v_readlane_b32 s5, v255, 21
	s_mov_b64 s[10:11], s[6:7]
	v_mov_b32_e32 v0, v203
	s_and_b32 s6, s1, 7
	s_cmp_lg_u32 s6, 0
	v_readfirstlane_b32 s8, v0
	s_cbranch_scc0 .LBB0_694
	s_cmpk_gt_i32 s0, 0x1ff
	s_cbranch_scc0 .LBB0_695
	s_branch .LBB0_697

; #define GSYNC() do { LAS unsigned char* l_ = (LAS unsigned char*)lds; asm volatile("" : "+s"(l_)); unsigned char* w_ = args.ws; asm volatile("" : "+s"(w_)); int t_ = threadIdx.x; asm volatile("" : "+v"(t_)); xcd_barrier((unsigned*)(w_ + WS_CTL), (volatile LAS unsigned*)(l_ + LDS_MISC), __builtin_amdgcn_readfirstlane(t_ >> 6), t_ & 63); } while (0)
; __global__ void __launch_bounds__(NTHREADS, 2) mega_fwd(Args args) {
;     ...
;         GSYNC();
;         {   PHASE_PTRS
;             pg8::Gemm g{(const bf16*)(ws + WS_QO), (const bf16*)(ws + WS_WOUT), M, DM, DM, DM, DM}; pg8::StaticOrder S; S.init(M, DM, G_, bx_);
;             EpiRes E{XB, SSQ, 1.0f};
;             pg8::gemm_phase<EpiRes, pg8::StaticOrder, true, true>(ldsp, g, S, E);
.LBB0_866:
	s_add_i32 s101, s101, 1
	v_readlane_b32 s8, v255, 20
	v_readlane_b32 s9, v255, 21
	v_readlane_b32 s10, v255, 22
	v_readlane_b32 s11, v255, 23
	s_mov_b32 s0, s83
	s_mov_b32 s1, s56
	s_mov_b32 s18, s69
	s_mov_b64 s[4:5], s[10:11]
	s_mov_b64 s[6:7], s[8:9]
	s_waitcnt lgkmcnt(0)
	s_barrier
	v_mov_b32_e32 v11, v203
	s_cmpk_lt_i32 s0, 0x100
	s_cselect_b64 s[6:7], -1, 0
	s_cmpk_gt_i32 s0, 0xff
	v_readfirstlane_b32 s16, v11
	s_cbranch_scc1 .LBB0_872
	s_ashr_i32 s2, s0, 31
	s_lshr_b32 s2, s2, 29
	s_add_i32 s2, s0, s2
	s_and_b32 s8, s2, -8
	s_sub_i32 s10, s0, s8
	s_cmp_gt_i32 s10, -1
	s_mov_b64 s[8:9], -1
	s_cbranch_scc0 .LBB0_869
	s_lshl_b32 s11, s10, 5
	s_mov_b64 s[8:9], 0

; #define LAS __attribute__((address_space(3)))
; #define GSYNC() do { LAS unsigned char* l_ = (LAS unsigned char*)lds; asm volatile("" : "+s"(l_)); unsigned char* w_ = args.ws; asm volatile("" : "+s"(w_)); int t_ = threadIdx.x; asm volatile("" : "+v"(t_)); xcd_barrier((unsigned*)(w_ + WS_CTL), (volatile LAS unsigned*)(l_ + LDS_MISC), __builtin_amdgcn_readfirstlane(t_ >> 6), t_ & 63); } while (0)
; __global__ void __launch_bounds__(NTHREADS, 2) mega_fwd(Args args) {
;     ...
;         GSYNC();
;         {   PHASE_PTRS
;             pg8::Gemm g{XB, (const bf16*)(ws + WS_WQK), M, DM, DM, DM, DM}; pg8::BatchOrder S; S.init(M, DM, G_, bx_); S.mb = SEQ / 256; S.bstride = (size_t)DM * DM * 2;
;             EpiSoftmax E{(bf16*)(ws + WS_PB), SSQ, (LAS float*)(ldsp + 131072)};
;             pg8::gemm_phase<EpiSoftmax, pg8::BatchOrder, true, true>(ldsp, g, S, E);
.LBB0_976:
	s_add_i32 s101, s101, 1
	v_readlane_b32 s4, v255, 20
	s_mov_b32 s0, s83
	s_mov_b32 s1, s56
	s_mov_b32 s14, s69
	v_readlane_b32 s5, v255, 21
	v_readlane_b32 s6, v255, 22
	v_readlane_b32 s7, v255, 23
	s_waitcnt lgkmcnt(0)
	s_barrier
	v_mov_b32_e32 v8, v203
	s_cmpk_lt_i32 s0, 0x100
	s_cselect_b64 s[4:5], -1, 0
	s_cmpk_gt_i32 s0, 0xff
	v_readfirstlane_b32 s12, v8
	s_cbranch_scc1 .LBB0_982
	s_ashr_i32 s2, s0, 31
	s_lshr_b32 s2, s2, 29
	s_add_i32 s2, s0, s2
	s_and_b32 s8, s2, -8
	s_sub_i32 s10, s0, s8
	s_cmp_gt_i32 s10, -1
	s_mov_b64 s[8:9], -1
	s_cbranch_scc0 .LBB0_979
	s_lshl_b32 s11, s10, 5
	s_mov_b64 s[8:9], 0

;     __host__ __device__ bool next(int i, Unit& u) const {
;         const long L = (long)i * G + c; if (L >= nwg) return false;
;         int wgid = (int)L; { const int q = nwg / NXCD, r = nwg % NXCD, xcd = wgid % NXCD, off = wgid / NXCD; wgid = (xcd < r ? xcd * (q + 1) : r * (q + 1) + (xcd - r) * q) + off; }
;         const int nig = WGM * nN, gid = wgid / nig, fm = gid * WGM, gsz = (nM - fm) < WGM ? (nM - fm) : WGM;
;         u.pm = fm + ((wgid % nig) % gsz); u.pn = (wgid % nig) / gsz; return true;
; template <class Epi, class Sched, bool ALIGN_EPI = false, bool SP2 = false>
; __device__ __forceinline__ void gemm_phase(PG8_LAS unsigned char* lds, const Gemm g, const Sched& S, const Epi& E) {
;     int tid_ = threadIdx.x; asm volatile("" : "+v"(tid_)); const int tid = tid_, wid = __builtin_amdgcn_readfirstlane(tid >> 6), lane = tid & 63, wr = wid >> 2, wc = wid & 3, fr = lane & 15, fq = lane >> 4;
;     const int K = g.K, nt = K / BK;
;     unsigned voffA[2], voffB[2];
; #pragma unroll
;     for (int i = 0; i < 2; ++i) { int R, C; stage_rc(tid * 16 + i * 8192, R, C); const int Rb = Epi::PERM ? ((R & ~31) + perm32(R & 31)) : R;
;         voffA[i] = (unsigned)(R * g.lda + C) * 2u; voffB[i] = (unsigned)(Rb * g.ldb + C) * 2u; }
;     const size_t kstep = (size_t)(BK * 2);
;     const size_t hstepA = (size_t)HALF * g.lda * 2, hstepB = (size_t)HALF * g.ldb * 2;
;     const size_t tstepA = 2 * hstepA, tstepB = 2 * hstepB;
;     const unsigned ldsw = (unsigned)wid * 1024u;
;     const int aoff = lds_byte(wr * 64 + fr, fq * 8), boff = lds_byte(wc * 32 + fr, fq * 8);
;     ...
;     Unit cur, nxt; int ui = 0;
;     if (!S.next(0, cur)) return;
;     f32x4 acc[2][2][4][2];
; #pragma unroll
;     for (int a = 0; a < 2; ++a)
; #pragma unroll
;         for (int b = 0; b < 2; ++b)
; #pragma unroll
;             for (int m = 0; m < 4; ++m)
; #pragma unroll
;                 for (int n = 0; n < 2; ++n) acc[a][b][m][n] = (f32x4){0.f, 0.f, 0.f, 0.f};
;     bf16x8 At[4][2], B0[2][2], B1[2][2];
;     const char* cA = (const char*)g.A + S.aoff(cur, tstepA); const char* cB = (const char*)g.Bt + S.boff(cur, tstepB);
;     S.a_ready(cur);
;     if constexpr (SP2) {
;         PG8_STAGE(PG8_SB(0, 0), cB, voffB); PG8_STAGE(PG8_SB(0, 1), cB + hstepB, voffB); PG8_STAGE(PG8_SA(0, 0), cA, voffA); PG8_STAGE(PG8_SA(0, 1), cA + hstepA, voffA);
;         if (wr == 1) PG8_BAR;
.LBB0_1212:
	s_add_i32 s101, s101, 1
	v_readlane_b32 s8, v255, 20
	v_readlane_b32 s9, v255, 21
	v_readlane_b32 s10, v255, 22
	v_readlane_b32 s11, v255, 23
	s_mov_b32 s0, s83
	s_mov_b32 s1, s56
	s_mov_b32 s12, s69
	s_mov_b64 s[4:5], s[10:11]
	s_mov_b64 s[6:7], s[8:9]
	v_mov_b32_e32 v14, v203
	s_waitcnt lgkmcnt(0)
	s_barrier
	s_cmpk_gt_i32 s0, 0x57f
	v_readfirstlane_b32 s10, v14
	s_cbranch_scc1 .LBB0_1228
	v_lshlrev_b32_e32 v0, 4, v14
	v_add_u32_e32 v1, 0x2000, v0
	v_ashrrev_i32_e32 v2, 31, v1
	v_lshrrev_b32_e32 v2, 22, v2
	v_add_u32_e32 v2, v1, v2
	v_ashrrev_i32_e32 v8, 10, v2
	v_mul_i32_i24_e32 v2, 0x400, v8
	v_sub_u32_e32 v1, v1, v2
	v_lshrrev_b32_e32 v2, 4, v1
	v_bitop3_b32 v1, v2, v1, 32 bitop3:0x6c
	v_ashrrev_i32_e32 v2, 31, v1
	v_lshrrev_b32_e32 v2, 26, v2
	v_add_u32_e32 v2, v1, v2
	v_lshlrev_b32_e32 v3, 3, v8
	v_ashrrev_i32_e32 v9, 6, v2
	v_and_b32_e32 v3, -16, v3
	v_add_u32_e32 v3, v9, v3
	v_and_b32_e32 v4, 3, v9
	s_mov_b32 s6, 0x1fffe0
	v_lshrrev_b32_e32 v5, 2, v3
	v_lshlrev_b32_e32 v6, 1, v3
	v_and_b32_e32 v2, 0xc0, v2
	v_and_or_b32 v4, v3, s6, v4
	v_and_b32_e32 v5, 4, v5
	v_and_b32_e32 v6, 24, v6
	v_sub_u32_e32 v1, v1, v2
	v_or3_b32 v4, v4, v5, v6
	v_lshlrev_b32_e32 v5, 5, v8
	v_ashrrev_i16_sdwa v1, v244, sext(v1) dst_sel:DWORD dst_unused:UNUSED_PAD src0_sel:DWORD src1_sel:BYTE_0
	v_and_b32_e32 v5, 32, v5
	v_bfe_i32 v10, v1, 0, 16
	v_add_lshl_u32 v1, v5, v10, 1
	v_lshl_add_u32 v128, v4, 11, v1
	v_lshl_add_u32 v130, v3, 11, v1
	v_bfe_i32 v1, v14, 27, 1
	v_lshrrev_b32_e32 v1, 22, v1
	v_add_u32_e32 v1, v0, v1
	v_and_b32_e32 v1, 0xfffffc00, v1
	v_sub_u32_e32 v0, v0, v1
	v_lshrrev_b32_e32 v1, 4, v0
	v_ashrrev_i32_e32 v2, 31, v14
	v_bitop3_b32 v0, v1, v0, 32 bitop3:0x6c
	v_lshrrev_b32_e32 v2, 26, v2
	v_ashrrev_i32_e32 v1, 31, v0
	v_add_u32_e32 v2, v14, v2
	s_add_u32 s28, s4, 0x3a00000
	v_lshrrev_b32_e32 v1, 26, v1
	v_ashrrev_i32_e32 v12, 6, v2
	s_addc_u32 s29, s5, 0
	v_add_u32_e32 v1, v0, v1
	v_lshlrev_b32_e32 v2, 3, v12
	s_add_u32 s30, s4, 0x2200000
	v_ashrrev_i32_e32 v11, 6, v1
	v_and_b32_e32 v2, -16, v2
	s_addc_u32 s31, s5, 0
	v_add_u32_e32 v2, v11, v2
	v_and_b32_e32 v3, 3, v11
	s_ashr_i32 s34, s0, 31
	v_and_or_b32 v3, v2, s6, v3
	s_lshr_b32 s6, s34, 29
	s_add_i32 s6, s0, s6
	s_ashr_i32 s13, s10, 6
	s_ashr_i32 s7, s6, 3
	s_and_b32 s6, s6, -8
	s_ashr_i32 s2, s10, 8
	s_lshl_b32 s11, s13, 10
	s_sub_i32 s6, s0, s6
	s_cmp_lt_i32 s6, 0
	s_movk_i32 s8, 0xb1
	s_cselect_b32 s8, s8, 0xb0
	s_mul_i32 s6, s6, s8
	s_add_i32 s6, s6, s7
	s_mul_hi_i32 s7, s6, 0x2e8ba2e9
	s_lshr_b32 s8, s7, 31
	s_ashr_i32 s7, s7, 5
	s_add_i32 s7, s7, s8
	s_lshl_b32 s9, s7, 3
	s_mulk_i32 s7, 0xb0
	s_sub_i32 s6, s6, s7
	s_bfe_u32 s7, s6, 0x3001c
	s_add_i32 s7, s6, s7
	s_sext_i32_i16 s8, s7
	s_and_b32 s7, s7, 0xfff8
	s_sub_i32 s6, s6, s7
	s_sext_i32_i16 s6, s6
	s_lshr_b32 s8, s8, 3
	s_add_i32 s20, s9, s6
	s_ashr_i32 s21, s20, 31
	s_bfe_i64 s[14:15], s[8:9], 0x100000
	s_lshl_b64 s[6:7], s[20:21], 19
	s_lshl_b64 s[14:15], s[14:15], 19
	s_add_u32 s22, s30, s14
	s_addc_u32 s23, s31, s15
	s_add_i32 s21, s12, 0x10000
	v_lshrrev_b32_e32 v4, 2, v2
	v_lshlrev_b32_e32 v5, 1, v2
	v_and_b32_e32 v1, 0xc0, v1
	s_add_i32 s35, s21, s11
	v_and_b32_e32 v4, 4, v4
	v_and_b32_e32 v5, 24, v5
	v_sub_u32_e32 v0, v0, v1
	s_add_i32 s36, s35, 0x2000
	v_or3_b32 v3, v3, v4, v5
	v_lshlrev_b32_e32 v4, 5, v12
	v_ashrrev_i16_sdwa v0, v244, sext(v0) dst_sel:DWORD dst_unused:UNUSED_PAD src0_sel:DWORD src1_sel:BYTE_0
	s_add_u32 s14, s22, 0x40000
	v_and_b32_e32 v4, 32, v4
	v_bfe_i32 v13, v0, 0, 16
	s_addc_u32 s15, s23, 0
	s_add_i32 s37, s12, 0x14000
	v_add_lshl_u32 v0, v4, v13, 1
	s_add_i32 s38, s37, s11
	v_lshl_add_u32 v192, v3, 11, v0
	s_mov_b32 m0, s35
	s_add_i32 s39, s38, 0x2000
	global_load_lds_dwordx4 v192, s[22:23]
	s_mov_b32 m0, s36
	s_add_u32 s24, s28, s6
	global_load_lds_dwordx4 v128, s[22:23]
	s_mov_b32 m0, s38
	s_addc_u32 s25, s29, s7
	s_add_i32 s40, s12, s11
	global_load_lds_dwordx4 v192, s[14:15]
	s_mov_b32 m0, s39
	s_add_i32 s41, s40, 0x2000
	v_lshl_add_u32 v132, v2, 11, v0
	global_load_lds_dwordx4 v128, s[14:15]
	s_mov_b32 m0, s40
	s_add_u32 s6, s24, 0x40000
	global_load_lds_dwordx4 v132, s[24:25]
	s_mov_b32 m0, s41
	s_addc_u32 s7, s25, 0
	s_add_i32 s42, s40, 0x4000
	global_load_lds_dwordx4 v130, s[24:25]
	s_mov_b32 m0, s42
	s_add_i32 s43, s40, 0x6000
	global_load_lds_dwordx4 v132, s[6:7]
	s_mov_b32 m0, s43
	v_mov_b32_e32 v129, v193
	global_load_lds_dwordx4 v130, s[6:7]
	v_mov_b32_e32 v133, v193
	v_mov_b32_e32 v131, v193
	s_cmp_eq_u32 s2, 1
	v_lshl_add_u64 v[6:7], s[22:23], 0, v[192:193]
	v_lshl_add_u64 v[4:5], s[22:23], 0, v[128:129]
	v_lshl_add_u64 v[0:1], s[24:25], 0, v[132:133]
	s_cselect_b64 s[6:7], -1, 0
	s_cmp_lg_u32 s2, 1
	v_lshl_add_u64 v[2:3], s[24:25], 0, v[130:131]
	s_cbranch_scc1 .LBB0_1215
	s_barrier

; __global__ void __launch_bounds__(NTHREADS, 2) mega_fwd(Args args) {
;     ...
;         {   PHASE_PTRS
;             const attn_body::AttnTensors AT{(const attn_body::bf16*)(ws + WS_QO) + 512, (const attn_body::bf16*)(ws + WS_FK), (const attn_body::bf16*)(ws + WS_FV), (attn_body::bf16*)(ws + WS_QO) + 512, (const float*)(ws + WS_C2), (const float*)(ws + WS_KMAX), (const float*)(ws + WS_QS)};
;             const attn_body::StaticOrder S(G_, bx_, (const int*)(ws + WS_ORD));
;             attn_body::attn_phase<attn_body::StaticOrder>((char*)ldsp, AT, S);
.LBB0_1296:
	s_add_i32 s101, s101, 1
	v_readlane_b32 s8, v255, 20
	v_readlane_b32 s9, v255, 21
	v_readlane_b32 s10, v255, 22
	v_readlane_b32 s11, v255, 23
	s_mov_b32 s0, s83
	s_mov_b32 s1, s56
	s_mov_b32 s18, s69
	s_mov_b64 s[4:5], s[10:11]
	s_mov_b64 s[6:7], s[8:9]
	s_waitcnt lgkmcnt(0)
	s_barrier
	v_mov_b32_e32 v12, v203
	s_cmpk_lt_i32 s0, 0x100
	s_cselect_b64 s[6:7], -1, 0
	s_cmpk_gt_i32 s0, 0xff
	v_readfirstlane_b32 s16, v12
	s_cbranch_scc1 .LBB0_1302
	s_ashr_i32 s2, s0, 31
	s_lshr_b32 s2, s2, 29
	s_add_i32 s2, s0, s2
	s_and_b32 s8, s2, -8
	s_sub_i32 s10, s0, s8
	s_cmp_gt_i32 s10, -1
	s_mov_b64 s[8:9], -1
	s_cbranch_scc0 .LBB0_1299
	s_lshl_b32 s11, s10, 5
	s_mov_b64 s[8:9], 0

; __device__ __forceinline__ unsigned xb_ld_u(unsigned* p) { return (unsigned)__builtin_amdgcn_readfirstlane((int)__hip_atomic_load(p, RLX_AGENT)); }
; __device__ __forceinline__ unsigned xb_add_u(unsigned* p, unsigned v, int lane) { unsigned r = 0u; if (lane == 0) r = __hip_atomic_fetch_add(p, v, RLX_AGENT); return (unsigned)__builtin_amdgcn_readfirstlane((int)r); }
; #define XB_SPIN_U(cond, bar) do { unsigned _sp = 0; while (cond) { __builtin_amdgcn_s_sleep(1); if (++_sp > XB_SPIN_CAP) { if (lane == 0) atomicAdd(&(bar)[XB_TMO], 1u); break; } } } while (0)
; __device__ __forceinline__ void xcd_barrier(unsigned* bar, volatile __attribute__((address_space(3))) unsigned* st, int wave, int lane) {
;     ...
;         const unsigned old = xb_add_u(&bar[XB_XSUB(x)], 1u, lane), gen = old / nloc;
;         if (old + 1u == (gen + 1u) * nloc) {
;             __builtin_amdgcn_fence(__ATOMIC_RELEASE, "agent");
;             asm volatile("s_waitcnt vmcnt(0)" ::: "memory");
;             const unsigned og = xb_add_u(&bar[XB_TOP], 1u, lane), tg = og / nx;
;             if (og + 1u == (tg + 1u) * nx) (void)xb_add_u(&bar[XB_TOPGEN], 1u, lane);
;             else XB_SPIN_U(xb_ld_u(&bar[XB_TOPGEN]) == tg, bar);
;             __builtin_amdgcn_fence(__ATOMIC_ACQUIRE, "agent");
;             (void)xb_add_u(&bar[XB_XGEN(x)], 1u, lane);
;             asm volatile("s_waitcnt vmcnt(0)" ::: "memory");
.LBB0_1407:
	v_mov_b32_e32 v0, s1
	v_add_co_u32_e32 v0, vcc, 0x2000, v0
	v_mov_b32_e32 v1, s0
	s_nop 0
	v_addc_co_u32_e32 v1, vcc, 0, v1, vcc
	s_nop 0
.Lrel_join_11:
	s_getpc_b64 s[98:99]
